# GDN prep 5a/5b: operand reads hoisted + independent accumulators; mLSTM prep: next unit's loads issued one unit ahead
# speedup vs baseline: 1.0127x; 1.0074x over previous
; #define LAS __attribute__((address_space(3)))
; __device__ __forceinline__ v2u pack4(const f32x4 v) { v2u r; r.x = pk2(v[0], v[1]); r.y = pk2(v[2], v[3]); return r; }
;     ...
;         {
;             const bool isw = w >= 4; const LAS bf16_t* Aop = isw ? T1 : T0; const LAS bf16_t* Bop = isw ? Kt : Vt;
;             LAS bf16_t* o0 = isw ? WT : UT; LAS bf16_t* o1 = isw ? WTd : UTd;
; #pragma unroll
;             for (int k4 = 0; k4 < 4; ++k4) { const int tt = (w & 3) * 4 + k4, mt = tt >> 2, nt = tt & 3;
;                 f32x4 acc = {0.f, 0.f, 0.f, 0.f}; acc = mma_ll<2>(Aop + mt * 16 * 72, 72, Bop + nt * 16 * 72, 72, acc, lane);
;                 const int n = nt * 16 + lr, m0 = mt * 16 + 4 * lq; f32x4 dv;
; #pragma unroll
;                 for (int i = 0; i < 4; ++i) dv[i] = acc[i] * gS[d * 64 + m0 + i];
;                 *(LAS v2u*)(o0 + n * 72 + m0) = pack4(acc); *(LAS v2u*)(o1 + n * 72 + m0) = pack4(dv); }
;         }
;         __syncthreads();
;         if (stop == 6) { __syncthreads(); continue; }
;         {
;             const int prod = w >> 1; bf16_t* gout = PGo + (size_t)ud * 16384 + prod * 4096;
;             const LAS bf16_t* Aop = prod == 0 ? WTd : prod == 1 ? Kt : prod == 2 ? WT : Ad;
;             const LAS bf16_t* Bop = prod == 0 ? Kt : prod == 1 ? UTd : prod == 2 ? Ad : UT;
;             v2u res[8];
; #pragma unroll
;             for (int k8 = 0; k8 < 8; ++k8) { const int tt = (w & 1) * 8 + k8, mt = tt >> 2, nt = tt & 3;
;                 f32x4 acc = {0.f, 0.f, 0.f, 0.f}; acc = mma_ll<2>(Aop + mt * 16 * 72, 72, Bop + nt * 16 * 72, 72, acc, lane);
.LBB0_646:
	s_mul_i32 s12, s9, 0x4800
	v_add_u32_e32 v0, s12, v63
	v_lshl_add_u32 v210, s9, 8, v110
	ds_read_b128 v[142:145], v0
	ds_read_b128 v[154:157], v108
	ds_read_b128 v[158:161], v108 offset:2304
	ds_read_b128 v[162:165], v108 offset:4608
	ds_read_b128 v[166:169], v108 offset:6912
	ds_read_b128 v[146:149], v0 offset:64
	ds_read_b128 v[170:173], v108 offset:64
	ds_read_b128 v[176:179], v108 offset:2368
	ds_read_b128 v[180:183], v108 offset:4672
	ds_read_b128 v[184:187], v108 offset:6976
	ds_read_b128 v[150:153], v210 offset:36864
	s_waitcnt vmcnt(18)
	s_lshl_b32 s12, s9, 2
	s_add_i32 s14, s12, 0
	s_waitcnt vmcnt(17)
	v_mov_b32_e32 v14, s14
	ds_read_b32 v133, v14 offset:38400
	v_lshl_add_u32 v18, s9, 8, v110
	s_mul_i32 s12, s9, 0x2400
	s_add_i32 s12, s12, 0
	s_waitcnt vmcnt(16)
	s_add_i32 s15, s12, 0x1b800
	s_and_b64 s[12:13], s[30:31], exec
	s_cselect_b32 s33, s1, s15
	s_and_b64 s[12:13], s[28:29], exec
	s_cselect_b32 s33, s3, s33
	s_and_b64 s[12:13], s[40:41], exec
	s_cselect_b32 s33, s76, s33
	s_and_b64 vcc, s[30:31], exec
	s_cselect_b32 s15, s15, s2
	s_and_b64 s[12:13], s[28:29], exec
	s_cselect_b32 s15, s77, s15
	s_and_b64 s[12:13], s[40:41], exec
	s_cselect_b32 s12, s3, s15
	v_add3_u32 v28, s12, v113, v117
	s_mul_i32 s12, s9, 0xfc
	s_add_i32 s14, s14, s12
	v_lshl_add_u32 v0, v109, 2, s14
	v_add3_u32 v10, s33, v113, v117
	v_add_u32_e32 v11, s0, v10
	s_waitcnt lgkmcnt(10)
	v_mfma_f32_16x16x32_bf16 v[188:191], v[142:145], v[154:157], 0
	s_waitcnt lgkmcnt(9)
	v_mfma_f32_16x16x32_bf16 v[192:195], v[142:145], v[158:161], 0
	s_waitcnt lgkmcnt(8)
	v_mfma_f32_16x16x32_bf16 v[196:199], v[142:145], v[162:165], 0
	s_waitcnt lgkmcnt(7)
	v_mfma_f32_16x16x32_bf16 v[200:203], v[142:145], v[166:169], 0
	s_waitcnt lgkmcnt(5)
	v_mfma_f32_16x16x32_bf16 v[188:191], v[146:149], v[170:173], v[188:191]
	s_waitcnt lgkmcnt(4)
	v_mfma_f32_16x16x32_bf16 v[192:195], v[146:149], v[176:179], v[192:195]
	s_waitcnt lgkmcnt(3)
	v_mfma_f32_16x16x32_bf16 v[196:199], v[146:149], v[180:183], v[196:199]
	s_waitcnt lgkmcnt(2)
	v_mfma_f32_16x16x32_bf16 v[200:203], v[146:149], v[184:187], v[200:203]
	s_waitcnt lgkmcnt(1)
	s_nop 3
	v_pk_mul_f32 v[204:205], v[188:189], v[150:151]
	v_pk_mul_f32 v[206:207], v[190:191], v[152:153]
	v_cvt_pk_bf16_f32 v208, v188, v189
	v_cvt_pk_bf16_f32 v209, v190, v191
	ds_write_b64 v61, v[208:209]
	v_cvt_pk_bf16_f32 v204, v204, v205
	v_cvt_pk_bf16_f32 v205, v206, v207
	ds_write_b64 v111, v[204:205]
	v_pk_mul_f32 v[204:205], v[192:193], v[150:151]
	v_pk_mul_f32 v[206:207], v[194:195], v[152:153]
	v_cvt_pk_bf16_f32 v208, v192, v193
	v_cvt_pk_bf16_f32 v209, v194, v195
	ds_write_b64 v112, v[208:209]
	v_cvt_pk_bf16_f32 v204, v204, v205
	v_cvt_pk_bf16_f32 v205, v206, v207
	ds_write_b64 v114, v[204:205]
	v_pk_mul_f32 v[204:205], v[196:197], v[150:151]
	v_pk_mul_f32 v[206:207], v[198:199], v[152:153]
	v_cvt_pk_bf16_f32 v208, v196, v197
	v_cvt_pk_bf16_f32 v209, v198, v199
	ds_write_b64 v115, v[208:209]
	v_cvt_pk_bf16_f32 v204, v204, v205
	v_cvt_pk_bf16_f32 v205, v206, v207
	ds_write_b64 v116, v[204:205]
	v_pk_mul_f32 v[204:205], v[200:201], v[150:151]
	v_pk_mul_f32 v[206:207], v[202:203], v[152:153]
	v_cvt_pk_bf16_f32 v208, v200, v201
	v_cvt_pk_bf16_f32 v209, v202, v203
	ds_write_b64 v118, v[208:209]
	v_cvt_pk_bf16_f32 v204, v204, v205
	v_cvt_pk_bf16_f32 v205, v206, v207
	ds_write_b64 v119, v[204:205]
	s_waitcnt lgkmcnt(0)
	s_barrier
	ds_read_b128 v[142:145], v11
	ds_read_b128 v[158:161], v28
	ds_read_b128 v[162:165], v28 offset:2304
	ds_read_b128 v[166:169], v28 offset:4608
	ds_read_b128 v[170:173], v28 offset:6912
	ds_read_b128 v[150:153], v11 offset:2304
	ds_read_b128 v[146:149], v11 offset:64
	ds_read_b128 v[176:179], v28 offset:64
	ds_read_b128 v[180:183], v28 offset:2368
	ds_read_b128 v[184:187], v28 offset:4672
	ds_read_b128 v[188:191], v28 offset:6976
	ds_read_b128 v[154:157], v11 offset:2368
	s_waitcnt lgkmcnt(10)
	v_mfma_f32_16x16x32_bf16 v[2:5], v[142:145], v[158:161], 0
	s_waitcnt lgkmcnt(9)
	v_mfma_f32_16x16x32_bf16 v[6:9], v[142:145], v[162:165], 0
	s_waitcnt lgkmcnt(8)
	v_mfma_f32_16x16x32_bf16 v[12:15], v[142:145], v[166:169], 0
	s_waitcnt lgkmcnt(7)
	v_mfma_f32_16x16x32_bf16 v[20:23], v[142:145], v[170:173], 0
	s_waitcnt lgkmcnt(6)
	v_mfma_f32_16x16x32_bf16 v[24:27], v[150:153], v[158:161], 0
	v_mfma_f32_16x16x32_bf16 v[16:19], v[150:153], v[162:165], 0
	v_mfma_f32_16x16x32_bf16 v[36:39], v[150:153], v[166:169], 0
	v_mfma_f32_16x16x32_bf16 v[28:31], v[150:153], v[170:173], 0
	s_waitcnt lgkmcnt(4)
	v_mfma_f32_16x16x32_bf16 v[2:5], v[146:149], v[176:179], v[2:5]
	s_waitcnt lgkmcnt(3)
	v_mfma_f32_16x16x32_bf16 v[6:9], v[146:149], v[180:183], v[6:9]
	s_waitcnt lgkmcnt(2)
	v_mfma_f32_16x16x32_bf16 v[12:15], v[146:149], v[184:187], v[12:15]
	s_waitcnt lgkmcnt(1)
	v_mfma_f32_16x16x32_bf16 v[20:23], v[146:149], v[188:191], v[20:23]
	s_waitcnt lgkmcnt(0)
	v_mfma_f32_16x16x32_bf16 v[24:27], v[154:157], v[176:179], v[24:27]
	v_mfma_f32_16x16x32_bf16 v[16:19], v[154:157], v[180:183], v[16:19]
	v_mfma_f32_16x16x32_bf16 v[36:39], v[154:157], v[184:187], v[36:39]
	v_mfma_f32_16x16x32_bf16 v[28:31], v[154:157], v[188:191], v[28:31]
	s_and_b64 vcc, exec, s[30:31]
	s_cbranch_vccz .L5b_plain
; #define LAS __attribute__((address_space(3)))
; __device__ __forceinline__ float fexp(float x) { return __builtin_amdgcn_exp2f(x * 1.4426950408889634f); }
; __device__ __forceinline__ v2u pack4(const f32x4 v) { v2u r; r.x = pk2(v[0], v[1]); r.y = pk2(v[2], v[3]); return r; }
; __device__ __forceinline__ f32x4 unpack4(const v2u w) { f32x4 r; r[0] = bflo(w.x); r[1] = bfhi(w.x); r[2] = bflo(w.y); r[3] = bfhi(w.y); return r; }
;     ...
;                 if (prod == 2) { const f32x4 qv = unpack4(*(const LAS v2u*)(Qs + n * 72 + m0)); const float e = 0.125f * fexp(gcS[d * 64 + n]); acc = qv * e - acc; }
;                 if (prod == 0) acc = -acc;
;                 res[k8] = pack4(acc); }
	v_add_u32_e32 v32, v121, v120
	v_add_u32_e32 v33, v122, v120
	ds_read_b32 v208, v0 offset:37888
	ds_read_b32 v210, v0 offset:37952
	ds_read_b32 v212, v0 offset:38016
	ds_read_b32 v214, v0 offset:38080
	ds_read_b64 v[192:193], v32
	ds_read_b64 v[194:195], v33
	ds_read_b64 v[196:197], v131
	ds_read_b64 v[198:199], v132
	ds_read_b64 v[200:201], v32 offset:32
	ds_read_b64 v[202:203], v33 offset:32
	ds_read_b64 v[204:205], v131 offset:32
	ds_read_b64 v[206:207], v132 offset:32
	s_waitcnt lgkmcnt(11)
	v_mul_f32_e32 v208, 0x3fb8aa3b, v208
	s_waitcnt lgkmcnt(10)
	v_mul_f32_e32 v210, 0x3fb8aa3b, v210
	s_waitcnt lgkmcnt(9)
	v_mul_f32_e32 v212, 0x3fb8aa3b, v212
	s_waitcnt lgkmcnt(8)
	v_mul_f32_e32 v214, 0x3fb8aa3b, v214
	v_exp_f32_e32 v208, v208
	v_exp_f32_e32 v210, v210
	v_exp_f32_e32 v212, v212
	v_exp_f32_e32 v214, v214
	v_mul_f32_e32 v208, 0x3e000000, v208
	v_mul_f32_e32 v210, 0x3e000000, v210
	v_mul_f32_e32 v212, 0x3e000000, v212
	v_mul_f32_e32 v214, 0x3e000000, v214
	s_waitcnt lgkmcnt(7)
	v_lshlrev_b32_e32 v216, 16, v192
	v_and_b32_e32 v217, 0xffff0000, v192
	v_lshlrev_b32_e32 v218, 16, v193
	v_and_b32_e32 v219, 0xffff0000, v193
	v_pk_fma_f32 v[2:3], v[208:209], v[216:217], v[2:3] op_sel_hi:[0,1,1] neg_lo:[0,0,1] neg_hi:[0,0,1]
	v_pk_fma_f32 v[4:5], v[208:209], v[218:219], v[4:5] op_sel_hi:[0,1,1] neg_lo:[0,0,1] neg_hi:[0,0,1]
	s_waitcnt lgkmcnt(6)
	v_lshlrev_b32_e32 v216, 16, v194
	v_and_b32_e32 v217, 0xffff0000, v194
	v_lshlrev_b32_e32 v218, 16, v195
	v_and_b32_e32 v219, 0xffff0000, v195
	v_pk_fma_f32 v[6:7], v[210:211], v[216:217], v[6:7] op_sel_hi:[0,1,1] neg_lo:[0,0,1] neg_hi:[0,0,1]
	v_pk_fma_f32 v[8:9], v[210:211], v[218:219], v[8:9] op_sel_hi:[0,1,1] neg_lo:[0,0,1] neg_hi:[0,0,1]
	s_waitcnt lgkmcnt(5)
	v_lshlrev_b32_e32 v216, 16, v196
	v_and_b32_e32 v217, 0xffff0000, v196
	v_lshlrev_b32_e32 v218, 16, v197
	v_and_b32_e32 v219, 0xffff0000, v197
	v_pk_fma_f32 v[12:13], v[212:213], v[216:217], v[12:13] op_sel_hi:[0,1,1] neg_lo:[0,0,1] neg_hi:[0,0,1]
	v_pk_fma_f32 v[14:15], v[212:213], v[218:219], v[14:15] op_sel_hi:[0,1,1] neg_lo:[0,0,1] neg_hi:[0,0,1]
	s_waitcnt lgkmcnt(4)
	v_lshlrev_b32_e32 v216, 16, v198
	v_and_b32_e32 v217, 0xffff0000, v198
	v_lshlrev_b32_e32 v218, 16, v199
	v_and_b32_e32 v219, 0xffff0000, v199
	v_pk_fma_f32 v[20:21], v[214:215], v[216:217], v[20:21] op_sel_hi:[0,1,1] neg_lo:[0,0,1] neg_hi:[0,0,1]
	v_pk_fma_f32 v[22:23], v[214:215], v[218:219], v[22:23] op_sel_hi:[0,1,1] neg_lo:[0,0,1] neg_hi:[0,0,1]
	s_waitcnt lgkmcnt(3)
	v_lshlrev_b32_e32 v216, 16, v200
	v_and_b32_e32 v217, 0xffff0000, v200
	v_lshlrev_b32_e32 v218, 16, v201
	v_and_b32_e32 v219, 0xffff0000, v201
	v_pk_fma_f32 v[24:25], v[208:209], v[216:217], v[24:25] op_sel_hi:[0,1,1] neg_lo:[0,0,1] neg_hi:[0,0,1]
	v_pk_fma_f32 v[26:27], v[208:209], v[218:219], v[26:27] op_sel_hi:[0,1,1] neg_lo:[0,0,1] neg_hi:[0,0,1]
	s_waitcnt lgkmcnt(2)
	v_lshlrev_b32_e32 v216, 16, v202
	v_and_b32_e32 v217, 0xffff0000, v202
	v_lshlrev_b32_e32 v218, 16, v203
	v_and_b32_e32 v219, 0xffff0000, v203
	v_pk_fma_f32 v[16:17], v[210:211], v[216:217], v[16:17] op_sel_hi:[0,1,1] neg_lo:[0,0,1] neg_hi:[0,0,1]
	v_pk_fma_f32 v[18:19], v[210:211], v[218:219], v[18:19] op_sel_hi:[0,1,1] neg_lo:[0,0,1] neg_hi:[0,0,1]
	s_waitcnt lgkmcnt(1)
	v_lshlrev_b32_e32 v216, 16, v204
	v_and_b32_e32 v217, 0xffff0000, v204
	v_lshlrev_b32_e32 v218, 16, v205
	v_and_b32_e32 v219, 0xffff0000, v205
	v_pk_fma_f32 v[36:37], v[212:213], v[216:217], v[36:37] op_sel_hi:[0,1,1] neg_lo:[0,0,1] neg_hi:[0,0,1]
	v_pk_fma_f32 v[38:39], v[212:213], v[218:219], v[38:39] op_sel_hi:[0,1,1] neg_lo:[0,0,1] neg_hi:[0,0,1]
	s_waitcnt lgkmcnt(0)
	v_lshlrev_b32_e32 v216, 16, v206
	v_and_b32_e32 v217, 0xffff0000, v206
	v_lshlrev_b32_e32 v218, 16, v207
	v_and_b32_e32 v219, 0xffff0000, v207
	v_pk_fma_f32 v[28:29], v[214:215], v[216:217], v[28:29] op_sel_hi:[0,1,1] neg_lo:[0,0,1] neg_hi:[0,0,1]
	v_pk_fma_f32 v[30:31], v[214:215], v[218:219], v[30:31] op_sel_hi:[0,1,1] neg_lo:[0,0,1] neg_hi:[0,0,1]
	s_branch .L5b_join
.L5b_plain:
	s_nop 7
; __device__ __forceinline__ v2u pack4(const f32x4 v) { v2u r; r.x = pk2(v[0], v[1]); r.y = pk2(v[2], v[3]); return r; }
; __device__ __forceinline__ void gdn_preload(const Frame& F, int u, int t, GdnPre& P) {
;     ...
;     if (t < 384) {
;         const int pair = t % 96, rg = t / 96, c0 = 2 * pair, part = c0 >> 6, d0 = c0 & 63, zcol = part * 256 + h * 64 + d0;
;         const int rbase = row0 + rg * 16 - 2; const bf16_t* zc = F.Z + zcol;
; #pragma unroll
;         for (int rr = 0; rr < 20; ++rr) { int row = rbase + rr; row = row < seg_lo ? seg_lo : (row >= seg_hi ? seg_hi - 1 : row); P.raw[rr] = *(const unsigned*)(zc + (size_t)row * ZW); }
;         P.ga = 0; P.gb = 0;
;     } else {
;         const int tt = t - 384, d = tt >> 6, pp = tt & 63; const bf16_t* zr = F.Z + (size_t)(row0 + pp) * ZW;
;         P.ga = zr[ZC_GA + d * 4 + h]; P.gb = zr[ZC_GB + d * 4 + h];
; #pragma unroll
;         for (int rr = 0; rr < 20; ++rr) P.raw[rr] = 0u;
;     ...
;                 if (prod == 0) acc = -acc;
;                 res[k8] = pack4(acc); }
;             asm volatile("" : "+v"(res[0]), "+v"(res[1]), "+v"(res[2]), "+v"(res[3]), "+v"(res[4]), "+v"(res[5]), "+v"(res[6]), "+v"(res[7]));
;             gdn_preload(F, u_next >= 0 ? u_next : u, t, P);
.L5b_join:
.LBB0_662:
	s_nop 2
	v_xor_b32_e32 v0, 0x80000000, v36
	v_xor_b32_e32 v10, 0x80000000, v37
	v_xor_b32_e32 v11, 0x80000000, v38
	v_xor_b32_e32 v32, 0x80000000, v39
	v_cndmask_b32_e64 v32, v39, v32, s[40:41]
	v_cndmask_b32_e64 v11, v38, v11, s[40:41]
	v_cndmask_b32_e64 v10, v37, v10, s[40:41]
	v_cndmask_b32_e64 v0, v36, v0, s[40:41]
	v_cvt_pk_bf16_f32 v10, v0, v10
	v_cvt_pk_bf16_f32 v11, v11, v32
	v_xor_b32_e32 v0, 0x80000000, v16
	v_xor_b32_e32 v32, 0x80000000, v17
	v_xor_b32_e32 v33, 0x80000000, v18
	v_cndmask_b32_e64 v17, v17, v32, s[40:41]
	v_cndmask_b32_e64 v0, v16, v0, s[40:41]
	v_cndmask_b32_e64 v33, v18, v33, s[40:41]
	v_cvt_pk_bf16_f32 v18, v0, v17
	v_xor_b32_e32 v0, 0x80000000, v24
	v_xor_b32_e32 v16, 0x80000000, v25
	v_cndmask_b32_e64 v16, v25, v16, s[40:41]
	v_cndmask_b32_e64 v0, v24, v0, s[40:41]
	v_cvt_pk_bf16_f32 v16, v0, v16
	v_xor_b32_e32 v0, 0x80000000, v20
	v_xor_b32_e32 v24, 0x80000000, v21
	v_xor_b32_e32 v25, 0x80000000, v22
	v_cndmask_b32_e64 v21, v21, v24, s[40:41]
	v_cndmask_b32_e64 v0, v20, v0, s[40:41]
	v_cndmask_b32_e64 v25, v22, v25, s[40:41]
	v_cvt_pk_bf16_f32 v22, v0, v21
	v_xor_b32_e32 v0, 0x80000000, v12
	v_xor_b32_e32 v20, 0x80000000, v13
	v_xor_b32_e32 v21, 0x80000000, v14
	v_xor_b32_e32 v24, 0x80000000, v15
	v_cndmask_b32_e64 v15, v15, v24, s[40:41]
	v_cndmask_b32_e64 v14, v14, v21, s[40:41]
	v_cndmask_b32_e64 v13, v13, v20, s[40:41]
	v_cndmask_b32_e64 v0, v12, v0, s[40:41]
	v_cvt_pk_bf16_f32 v20, v0, v13
	v_cvt_pk_bf16_f32 v21, v14, v15
	v_xor_b32_e32 v0, 0x80000000, v6
	v_xor_b32_e32 v12, 0x80000000, v7
	v_xor_b32_e32 v13, 0x80000000, v8
	v_xor_b32_e32 v14, 0x80000000, v9
	v_cndmask_b32_e64 v9, v9, v14, s[40:41]
	v_cndmask_b32_e64 v8, v8, v13, s[40:41]
	v_cndmask_b32_e64 v7, v7, v12, s[40:41]
	v_cndmask_b32_e64 v0, v6, v0, s[40:41]
	v_cvt_pk_bf16_f32 v6, v0, v7
	v_cvt_pk_bf16_f32 v7, v8, v9
	v_xor_b32_e32 v0, 0x80000000, v2
	v_xor_b32_e32 v8, 0x80000000, v3
	v_xor_b32_e32 v17, 0x80000000, v26
	v_xor_b32_e32 v9, 0x80000000, v4
	v_cndmask_b32_e64 v3, v3, v8, s[40:41]
	v_cndmask_b32_e64 v0, v2, v0, s[40:41]
	v_xor_b32_e32 v34, 0x80000000, v19
	v_xor_b32_e32 v32, 0x80000000, v27
	v_cndmask_b32_e64 v17, v26, v17, s[40:41]
	v_xor_b32_e32 v26, 0x80000000, v23
	v_xor_b32_e32 v12, 0x80000000, v5
	v_cndmask_b32_e64 v9, v4, v9, s[40:41]
	v_cvt_pk_bf16_f32 v4, v0, v3
	v_xor_b32_e32 v0, 0x80000000, v28
	v_xor_b32_e32 v2, 0x80000000, v29
	v_xor_b32_e32 v3, 0x80000000, v30
	v_xor_b32_e32 v8, 0x80000000, v31
	v_cndmask_b32_e64 v19, v19, v34, s[40:41]
	v_cndmask_b32_e64 v27, v27, v32, s[40:41]
	v_cndmask_b32_e64 v23, v23, v26, s[40:41]
	v_cndmask_b32_e64 v5, v5, v12, s[40:41]
	v_cndmask_b32_e64 v8, v31, v8, s[40:41]
	v_cndmask_b32_e64 v3, v30, v3, s[40:41]
	v_cndmask_b32_e64 v2, v29, v2, s[40:41]
	v_cndmask_b32_e64 v0, v28, v0, s[40:41]
	v_cvt_pk_bf16_f32 v19, v33, v19
	v_cvt_pk_bf16_f32 v17, v17, v27
	v_cvt_pk_bf16_f32 v23, v25, v23
	v_cvt_pk_bf16_f32 v5, v9, v5
	v_cvt_pk_bf16_f32 v12, v0, v2
	v_cvt_pk_bf16_f32 v13, v3, v8
	s_and_saveexec_b64 s[12:13], s[38:39]
	s_xor_b64 s[12:13], exec, s[12:13]
	s_cbranch_execz .LBB0_664
	s_waitcnt vmcnt(0)
	v_mov_b32_e32 v2, v220
	v_mov_b32_e32 v3, v221
.LBB0_664:
	s_or_saveexec_b64 s[44:45], s[12:13]
	v_mov_b32_e32 v59, 0
	v_mov_b32_e32 v58, 0
	v_mov_b32_e32 v56, 0
	v_mov_b32_e32 v55, 0
	v_mov_b32_e32 v27, 0
	v_mov_b32_e32 v26, 0
	v_mov_b32_e32 v25, 0
	v_mov_b32_e32 v24, 0
	v_mov_b32_e32 v15, 0
	v_mov_b32_e32 v14, 0
	v_mov_b32_e32 v9, 0
	v_mov_b32_e32 v8, 0
	v_mov_b32_e32 v134, 0
	s_waitcnt vmcnt(6)
	v_mov_b32_e32 v135, 0
	s_waitcnt vmcnt(5)
	v_mov_b32_e32 v136, 0
	s_waitcnt vmcnt(4)
	v_mov_b32_e32 v137, 0
	s_waitcnt vmcnt(3)
	v_mov_b32_e32 v138, 0
	s_waitcnt vmcnt(2)
	v_mov_b32_e32 v139, 0
	s_waitcnt vmcnt(1)
	v_mov_b32_e32 v140, 0
	s_waitcnt vmcnt(0)
	v_mov_b32_e32 v141, 0
	s_xor_b64 exec, exec, s[44:45]
	s_cbranch_execz .LBB0_666
	s_cmp_eq_u32 s9, 0
	s_cbranch_scc1 .LBB0_666
	global_load_dword v8, v[68:69], off
	global_load_dword v9, v[70:71], off
	global_load_dword v14, v[72:73], off
	global_load_dword v15, v[74:75], off
	global_load_dword v24, v[76:77], off
	global_load_dword v25, v[78:79], off
	global_load_dword v26, v[80:81], off
	global_load_dword v27, v[82:83], off
	global_load_dword v55, v[84:85], off
	global_load_dword v56, v[86:87], off
	global_load_dword v58, v[88:89], off
	global_load_dword v59, v[90:91], off
	global_load_dword v134, v[92:93], off
	global_load_dword v135, v[94:95], off
	global_load_dword v136, v[96:97], off
	global_load_dword v137, v[98:99], off
	global_load_dword v138, v[100:101], off
	global_load_dword v139, v[102:103], off
	global_load_dword v140, v[104:105], off
	global_load_dword v141, v[106:107], off
	v_mov_b32_e32 v2, 0
	v_mov_b32_e32 v3, 0

; #define LAS __attribute__((address_space(3)))
; __device__ __forceinline__ float logsigf_(float x) { return x >= 0.f ? -flog1p(fexp(-x)) : x - flog1p(fexp(x)); }
; __device__ __forceinline__ void mlstm_prep_unit(const Frame& F, int l, int u) {
;     ...
;     {
;         const int r = t >> 3, seg = t & 7; const bf16_t* zr = F.Z + (size_t)(row0 + r) * ZW + h * 64 + seg * 8;
;         const v4u q = *(const v4u*)(zr + ZC_LQ), k = *(const v4u*)(zr + ZC_LK), v = *(const v4u*)(zr + ZC_LV);
;         *(LAS v4u*)(Qs + r * 72 + seg * 8) = q; *(LAS v4u*)(Ks + r * 72 + seg * 8) = k;
;         Vta[( 0 + 2 * seg) * 72 + r] = (bf16_t)(v.x & 0xffffu); Vta[(16 + 2 * seg) * 72 + r] = (bf16_t)(v.x >> 16);
;         Vta[(32 + 2 * seg) * 72 + r] = (bf16_t)(v.y & 0xffffu); Vta[(48 + 2 * seg) * 72 + r] = (bf16_t)(v.y >> 16);
;         Vta[( 1 + 2 * seg) * 72 + r] = (bf16_t)(v.z & 0xffffu); Vta[(17 + 2 * seg) * 72 + r] = (bf16_t)(v.z >> 16);
;         Vta[(33 + 2 * seg) * 72 + r] = (bf16_t)(v.w & 0xffffu); Vta[(49 + 2 * seg) * 72 + r] = (bf16_t)(v.w >> 16);
; #pragma unroll
;         for (int j = 0; j < 2; ++j) { const int idx = t + 512 * j, rr = 64 + (idx >> 6), cc = idx & 63; Vta[rr * 72 + cc] = (bf16_t)(rr == 64 ? 0x3F80u : 0u); }
;         if (t < 128) { const int d = t >> 6, p = t & 63; const bf16_t* zg = F.Z + (size_t)(row0 + p) * ZW;
;             igS[d * 64 + p] = bf2f(zg[ZC_LI + d * 4 + h]) + F.ig_bias[l * 8 + d * 4 + h];
;             lfS[d * 64 + p] = logsigf_(bf2f(zg[ZC_LF + d * 4 + h]) + F.fg_bias[l * 8 + d * 4 + h]); }
;         if (t >= 128 && t < 272) chS[t - 128] = F.CHS[(size_t)((b * 4 + h) * 2) * 72 + (t - 128)];
.LBB0_688:
	s_mov_b32 s0, 0
	v_mbcnt_lo_u32_b32 v197, -1, 0
	v_mbcnt_hi_u32_b32 v197, -1, v197
	v_add_u32_e32 v198, s64, v197
	s_mov_b32 s20, s88
	s_mul_hi_i32 s21, s20, 0x38e38e39
	s_ashr_i32 s22, s21, 5
	s_lshr_b32 s23, s21, 31
	s_ashr_i32 s21, s21, 3
	s_add_i32 s21, s21, s23
	s_add_i32 s22, s22, s23
	s_mul_i32 s23, s21, 36
	s_sub_i32 s23, s20, s23
	s_and_b32 s25, s21, 3
	s_lshl_b32 s26, s23, 6
	s_lshl_b32 s24, s22, 11
	s_add_i32 s24, s24, s26
	s_add_i32 s24, s24, 0xffffff00
	s_lshl_b32 s27, s22, 8
	s_add_i32 s27, s27, s26
	s_add_i32 s27, s27, 0x4000
	s_cmp_gt_i32 s23, 3
	s_cselect_b32 s24, s24, s27
	v_ashrrev_i32_e32 v144, 3, v198
	v_add_u32_e32 v144, s24, v144
	v_mov_b64_e32 v[146:147], s[16:17]
	v_mad_i64_i32 v[146:147], s[8:9], v144, s66, v[146:147]
	s_lshl_b32 s26, s25, 7
	s_mov_b32 s27, 0
	v_lshl_add_u64 v[146:147], v[146:147], 0, s[26:27]
	v_and_b32_e32 v144, 7, v197
	v_lshlrev_b32_e32 v144, 4, v144
	v_mov_b32_e32 v145, 0
	v_lshl_add_u64 v[146:147], v[146:147], 0, v[144:145]
	s_movk_i32 s26, 0x1000
	v_lshl_add_u64 v[146:147], v[146:147], 0, s[26:27]
	global_load_dwordx4 v[180:183], v[146:147], off
	global_load_dwordx4 v[184:187], v[146:147], off offset:512
	global_load_dwordx4 v[188:191], v[146:147], off offset:1024
	s_cmp_lt_u32 s64, 0x80
	s_cbranch_scc0 .Lmn_p_a
	v_add_u32_e32 v144, s24, v197
	v_mov_b64_e32 v[146:147], s[16:17]
	v_mad_i64_i32 v[146:147], s[8:9], v144, s66, v[146:147]
	v_ashrrev_i32_e32 v144, 6, v198
	v_lshlrev_b32_e32 v144, 2, v144
	v_or_b32_e32 v145, s25, v144
	v_add_u32_e32 v148, 0xc10, v145
	v_ashrrev_i32_e32 v149, 31, v148
	v_lshl_add_u64 v[146:147], v[148:149], 1, v[146:147]
	global_load_ushort v192, v[146:147], off
	global_load_ushort v193, v[146:147], off offset:16
	v_add_u32_e32 v144, s68, v144
	v_or_b32_e32 v148, s25, v144
	v_ashrrev_i32_e32 v149, 31, v148
	v_lshlrev_b64 v[148:149], 2, v[148:149]
	v_lshl_add_u64 v[146:147], s[52:53], 0, v[148:149]
	global_load_dword v194, v[146:147], off
	v_lshl_add_u64 v[146:147], s[54:55], 0, v[148:149]
	global_load_dword v195, v[146:147], off
.Lmn_p_a:
	v_add_u32_e32 v145, 0xffffff80, v198
	s_movk_i32 s28, 0x90
	v_cmp_gt_u32_e64 s[32:33], s28, v145
	s_and_saveexec_b64 s[36:37], s[32:33]
	s_cbranch_execz .Lmn_p_b
	s_lshl_b32 s28, s22, 3
	s_lshl_b32 s29, s25, 1
	s_or_b32 s28, s29, s28
	s_mul_hi_i32 s29, s28, 0x120
	s_mulk_i32 s28, 0x120
	s_add_u32 s28, s18, s28
	s_addc_u32 s29, s19, s29
	v_mov_b32_e32 v146, v145
	v_mov_b32_e32 v147, 0
	v_lshl_add_u64 v[146:147], v[146:147], 2, s[28:29]
	global_load_dword v196, v[146:147], off
.Lmn_p_b:
	s_or_b64 exec, exec, s[36:37]
	s_branch .LBB0_690

; #define LAS __attribute__((address_space(3)))
; __device__ __forceinline__ void mlstm_prep_unit(const Frame& F, int l, int u) {
;     ...
;         const int r = t >> 3, seg = t & 7; const bf16_t* zr = F.Z + (size_t)(row0 + r) * ZW + h * 64 + seg * 8;
;         const v4u q = *(const v4u*)(zr + ZC_LQ), k = *(const v4u*)(zr + ZC_LK), v = *(const v4u*)(zr + ZC_LV);
;         *(LAS v4u*)(Qs + r * 72 + seg * 8) = q; *(LAS v4u*)(Ks + r * 72 + seg * 8) = k;
;         Vta[( 0 + 2 * seg) * 72 + r] = (bf16_t)(v.x & 0xffffu); Vta[(16 + 2 * seg) * 72 + r] = (bf16_t)(v.x >> 16);
;         Vta[(32 + 2 * seg) * 72 + r] = (bf16_t)(v.y & 0xffffu); Vta[(48 + 2 * seg) * 72 + r] = (bf16_t)(v.y >> 16);
;         Vta[( 1 + 2 * seg) * 72 + r] = (bf16_t)(v.z & 0xffffu); Vta[(17 + 2 * seg) * 72 + r] = (bf16_t)(v.z >> 16);
;         Vta[(33 + 2 * seg) * 72 + r] = (bf16_t)(v.w & 0xffffu); Vta[(49 + 2 * seg) * 72 + r] = (bf16_t)(v.w >> 16);
; #pragma unroll
;         for (int j = 0; j < 2; ++j) { const int idx = t + 512 * j, rr = 64 + (idx >> 6), cc = idx & 63; Vta[rr * 72 + cc] = (bf16_t)(rr == 64 ? 0x3F80u : 0u); }
.LBB0_694:
	s_waitcnt vmcnt(9)
	v_mbcnt_lo_u32_b32 v58, -1, 0
	v_mbcnt_hi_u32_b32 v58, -1, v58
	s_and_b32 s6, s3, 3
	v_add_u32_e32 v2, s64, v58
	v_ashrrev_i32_e32 v18, 3, v2
	v_add_u32_e32 v0, s7, v18
	v_mov_b64_e32 v[4:5], s[16:17]
	v_and_b32_e32 v3, 7, v58
	v_mad_i64_i32 v[4:5], s[8:9], v0, s66, v[4:5]
	s_lshl_b32 s92, s6, 7
	v_lshl_add_u64 v[4:5], v[4:5], 0, s[92:93]
	v_lshlrev_b32_e32 v0, 4, v3
	v_lshl_add_u64 v[4:5], v[4:5], 0, v[0:1]
	s_movk_i32 s3, 0x1000
	v_add_co_u32_e32 v4, vcc, s3, v4
	v_add_u32_e32 v20, 0x200, v2
	s_nop 0
	v_addc_co_u32_e32 v5, vcc, 0, v5, vcc
	s_movk_i32 s8, 0x90
	v_ashrrev_i32_e32 v4, 6, v2
	v_cmp_gt_u32_e32 vcc, 64, v2
	v_mul_lo_u32 v21, v18, s8
	v_ashrrev_i32_e32 v23, 6, v20
	v_and_b32_e32 v62, 63, v58
	v_cndmask_b32_e32 v19, 0, v230, vcc
	v_mul_lo_u32 v22, v4, s8
	v_cmp_gt_u32_e32 vcc, 64, v20
	v_add3_u32 v0, 0, v21, v0
	v_mul_lo_u32 v21, v23, s8
	s_movk_i32 s8, 0x80
	v_mul_u32_u24_e32 v5, 0x120, v3
	v_lshlrev_b32_e32 v3, 1, v62
	v_readfirstlane_b32 s3, v4
	v_lshlrev_b32_e32 v18, 1, v18
	v_cndmask_b32_e32 v20, 0, v230, vcc
	v_cmp_gt_i32_e32 vcc, s8, v2
	v_add3_u32 v5, 0, v5, v18
	v_add3_u32 v18, 0, v22, v3
	v_add3_u32 v21, 0, v21, v3
	s_cmp_lg_u32 s0, 0
	s_cbranch_scc1 .Lmn_w6
	s_waitcnt vmcnt(0)
	s_branch .Lmn_wd

; #define LAS __attribute__((address_space(3)))
; __device__ __forceinline__ float logsigf_(float x) { return x >= 0.f ? -flog1p(fexp(-x)) : x - flog1p(fexp(x)); }
; __device__ __forceinline__ void mlstm_prep_unit(const Frame& F, int l, int u) {
;     ...
;         *(LAS v4u*)(Qs + r * 72 + seg * 8) = q; *(LAS v4u*)(Ks + r * 72 + seg * 8) = k;
;         Vta[( 0 + 2 * seg) * 72 + r] = (bf16_t)(v.x & 0xffffu); Vta[(16 + 2 * seg) * 72 + r] = (bf16_t)(v.x >> 16);
;         Vta[(32 + 2 * seg) * 72 + r] = (bf16_t)(v.y & 0xffffu); Vta[(48 + 2 * seg) * 72 + r] = (bf16_t)(v.y >> 16);
;         Vta[( 1 + 2 * seg) * 72 + r] = (bf16_t)(v.z & 0xffffu); Vta[(17 + 2 * seg) * 72 + r] = (bf16_t)(v.z >> 16);
;         Vta[(33 + 2 * seg) * 72 + r] = (bf16_t)(v.w & 0xffffu); Vta[(49 + 2 * seg) * 72 + r] = (bf16_t)(v.w >> 16);
; #pragma unroll
;         for (int j = 0; j < 2; ++j) { const int idx = t + 512 * j, rr = 64 + (idx >> 6), cc = idx & 63; Vta[rr * 72 + cc] = (bf16_t)(rr == 64 ? 0x3F80u : 0u); }
;         if (t < 128) { const int d = t >> 6, p = t & 63; const bf16_t* zg = F.Z + (size_t)(row0 + p) * ZW;
;             igS[d * 64 + p] = bf2f(zg[ZC_LI + d * 4 + h]) + F.ig_bias[l * 8 + d * 4 + h];
;             lfS[d * 64 + p] = logsigf_(bf2f(zg[ZC_LF + d * 4 + h]) + F.fg_bias[l * 8 + d * 4 + h]); }
.Lmn_wd:
	ds_write_b128 v0, v[180:183]
	ds_write_b128 v0, v[184:187] offset:9216
	ds_write_b16 v5, v188 offset:18432
	ds_write_b16_d16_hi v5, v188 offset:20736
	ds_write_b16 v5, v189 offset:23040
	ds_write_b16_d16_hi v5, v189 offset:25344
	ds_write_b16 v5, v190 offset:18576
	ds_write_b16_d16_hi v5, v190 offset:20880
	ds_write_b16 v5, v191 offset:23184
	ds_write_b16_d16_hi v5, v191 offset:25488
	ds_write_b16 v18, v19 offset:27648
	ds_write_b16 v21, v20 offset:27648
	s_and_saveexec_b64 s[10:11], vcc
	s_cbranch_execz .LBB0_708
	v_lshlrev_b32_e32 v11, 16, v192
	s_waitcnt lgkmcnt(0)
	v_add_f32_e32 v8, v194, v11
	v_lshl_add_u32 v0, v2, 2, 0
	v_add_u32_e32 v9, 0x10500, v0
	ds_write_b32 v9, v8
	v_lshlrev_b32_e32 v6, 16, v193
	v_add_f32_e32 v4, v195, v6
	v_cmp_le_f32_e32 vcc, 0, v4
	s_and_saveexec_b64 s[8:9], vcc
	s_xor_b64 s[12:13], exec, s[8:9]
	s_cbranch_execz .LBB0_701
	v_mul_f32_e32 v4, 0xbfb8aa3b, v4
	v_exp_f32_e32 v4, v4
	s_mov_b32 s7, 0x3ca3d70a
	v_cmp_ngt_f32_e32 vcc, s7, v4
	s_and_saveexec_b64 s[8:9], vcc
	s_xor_b64 s[14:15], exec, s[8:9]
	v_add_f32_e32 v4, 1.0, v4
	v_log_f32_e32 v4, v4
	s_nop 0
	v_mul_f32_e32 v5, 0x3f317218, v4
	s_andn2_saveexec_b64 s[14:15], s[14:15]
	v_fmamk_f32 v5, v4, 0xbe800000, v222
	v_fma_f32 v5, -v4, v5, 0.5
	v_fma_f32 v5, -v4, v5, 1.0
	v_mul_f32_e32 v5, v4, v5
	s_or_b64 exec, exec, s[14:15]
	v_xor_b32_e32 v5, 0x80000000, v5

; #define LAS __attribute__((address_space(3)))
; __device__ __forceinline__ float logsigf_(float x) { return x >= 0.f ? -flog1p(fexp(-x)) : x - flog1p(fexp(x)); }
; __device__ __forceinline__ void mlstm_prep_unit(const Frame& F, int l, int u) {
;     ...
;     {
;         const int r = t >> 3, seg = t & 7; const bf16_t* zr = F.Z + (size_t)(row0 + r) * ZW + h * 64 + seg * 8;
;         const v4u q = *(const v4u*)(zr + ZC_LQ), k = *(const v4u*)(zr + ZC_LK), v = *(const v4u*)(zr + ZC_LV);
;         *(LAS v4u*)(Qs + r * 72 + seg * 8) = q; *(LAS v4u*)(Ks + r * 72 + seg * 8) = k;
;         Vta[( 0 + 2 * seg) * 72 + r] = (bf16_t)(v.x & 0xffffu); Vta[(16 + 2 * seg) * 72 + r] = (bf16_t)(v.x >> 16);
;         Vta[(32 + 2 * seg) * 72 + r] = (bf16_t)(v.y & 0xffffu); Vta[(48 + 2 * seg) * 72 + r] = (bf16_t)(v.y >> 16);
;         Vta[( 1 + 2 * seg) * 72 + r] = (bf16_t)(v.z & 0xffffu); Vta[(17 + 2 * seg) * 72 + r] = (bf16_t)(v.z >> 16);
;         Vta[(33 + 2 * seg) * 72 + r] = (bf16_t)(v.w & 0xffffu); Vta[(49 + 2 * seg) * 72 + r] = (bf16_t)(v.w >> 16);
; #pragma unroll
;         for (int j = 0; j < 2; ++j) { const int idx = t + 512 * j, rr = 64 + (idx >> 6), cc = idx & 63; Vta[rr * 72 + cc] = (bf16_t)(rr == 64 ? 0x3F80u : 0u); }
;         if (t < 128) { const int d = t >> 6, p = t & 63; const bf16_t* zg = F.Z + (size_t)(row0 + p) * ZW;
;             igS[d * 64 + p] = bf2f(zg[ZC_LI + d * 4 + h]) + F.ig_bias[l * 8 + d * 4 + h];
;             lfS[d * 64 + p] = logsigf_(bf2f(zg[ZC_LF + d * 4 + h]) + F.fg_bias[l * 8 + d * 4 + h]); }
;         if (t >= 128 && t < 272) chS[t - 128] = F.CHS[(size_t)((b * 4 + h) * 2) * 72 + (t - 128)];
;     }
;     __syncthreads();
.LBB0_708:
	s_or_b64 exec, exec, s[10:11]
	v_add_u32_e32 v0, 0xffffff80, v2
	s_movk_i32 s7, 0x90
	v_cmp_gt_u32_e32 vcc, s7, v0
	s_and_saveexec_b64 s[10:11], vcc
	s_cbranch_execz .LBB0_710
	v_lshl_add_u32 v0, v0, 2, 0
	v_add_u32_e32 v0, 0x11320, v0
	ds_write_b32 v0, v196
.LBB0_710:
	s_or_b64 exec, exec, s[10:11]
	s_cmp_gt_i32 s3, 1
	s_waitcnt lgkmcnt(0)
	s_barrier
	s_add_i32 s20, s0, 1
	s_cmp_eq_u32 s20, s81
	s_cbranch_scc1 .Lmn_skip
	s_add_i32 s20, s1, 1
	s_mul_hi_i32 s21, s20, 0x38e38e39
	s_ashr_i32 s22, s21, 5
	s_lshr_b32 s23, s21, 31
	s_ashr_i32 s21, s21, 3
	s_add_i32 s21, s21, s23
	s_add_i32 s22, s22, s23
	s_mul_i32 s23, s21, 36
	s_sub_i32 s23, s20, s23
	s_and_b32 s25, s21, 3
	s_lshl_b32 s26, s23, 6
	s_lshl_b32 s24, s22, 11
	s_add_i32 s24, s24, s26
	s_add_i32 s24, s24, 0xffffff00
	s_lshl_b32 s27, s22, 8
	s_add_i32 s27, s27, s26
	s_add_i32 s27, s27, 0x4000
	s_cmp_gt_i32 s23, 3
	s_cselect_b32 s24, s24, s27
	v_ashrrev_i32_e32 v144, 3, v2
	v_add_u32_e32 v144, s24, v144
	v_mov_b64_e32 v[146:147], s[16:17]
	v_mad_i64_i32 v[146:147], s[8:9], v144, s66, v[146:147]
	s_lshl_b32 s26, s25, 7
	s_mov_b32 s27, 0
	v_lshl_add_u64 v[146:147], v[146:147], 0, s[26:27]
	v_and_b32_e32 v144, 7, v58
	v_lshlrev_b32_e32 v144, 4, v144
	v_mov_b32_e32 v145, 0
	v_lshl_add_u64 v[146:147], v[146:147], 0, v[144:145]
	s_movk_i32 s26, 0x1000
	v_lshl_add_u64 v[146:147], v[146:147], 0, s[26:27]
	global_load_dwordx4 v[180:183], v[146:147], off
	global_load_dwordx4 v[184:187], v[146:147], off offset:512
	global_load_dwordx4 v[188:191], v[146:147], off offset:1024
	s_cmp_lt_u32 s64, 0x80
	s_cbranch_scc0 .Lmn_n_a
	v_add_u32_e32 v144, s24, v58
	v_mov_b64_e32 v[146:147], s[16:17]
	v_mad_i64_i32 v[146:147], s[8:9], v144, s66, v[146:147]
	v_ashrrev_i32_e32 v144, 6, v2
	v_lshlrev_b32_e32 v144, 2, v144
	v_or_b32_e32 v145, s25, v144
	v_add_u32_e32 v148, 0xc10, v145
	v_ashrrev_i32_e32 v149, 31, v148
	v_lshl_add_u64 v[146:147], v[148:149], 1, v[146:147]
	global_load_ushort v192, v[146:147], off
	global_load_ushort v193, v[146:147], off offset:16
	v_add_u32_e32 v144, s68, v144
	v_or_b32_e32 v148, s25, v144
	v_ashrrev_i32_e32 v149, 31, v148
	v_lshlrev_b64 v[148:149], 2, v[148:149]
	v_lshl_add_u64 v[146:147], s[52:53], 0, v[148:149]
	global_load_dword v194, v[146:147], off
	v_lshl_add_u64 v[146:147], s[54:55], 0, v[148:149]
	global_load_dword v195, v[146:147], off
.Lmn_n_a:
	v_add_u32_e32 v145, 0xffffff80, v2
	s_movk_i32 s28, 0x90
	v_cmp_gt_u32_e64 s[32:33], s28, v145
	s_and_saveexec_b64 s[36:37], s[32:33]
	s_cbranch_execz .Lmn_n_b
	s_lshl_b32 s28, s22, 3
	s_lshl_b32 s29, s25, 1
	s_or_b32 s28, s29, s28
	s_mul_hi_i32 s29, s28, 0x120
	s_mulk_i32 s28, 0x120
	s_add_u32 s28, s18, s28
	s_addc_u32 s29, s19, s29
	v_mov_b32_e32 v146, v145
	v_mov_b32_e32 v147, 0
	v_lshl_add_u64 v[146:147], v[146:147], 2, s[28:29]
	global_load_dword v196, v[146:147], off
.Lmn_n_b:
	s_or_b64 exec, exec, s[36:37]
; __device__ __forceinline__ void mlstm_prep_unit(const Frame& F, int l, int u) {
;     ...
;     __syncthreads();
;     if (w < 2) {
;         const int d = w, p = d ? 63 - lane : lane;
;         const int step_of = d ? (cidx < 4 ? 3 - cidx : 39 - cidx) : cidx; float mprev = 0.f;
;         for (int s = 0; s < step_of; ++s) { const int ci = d ? (s < 4 ? 3 - s : 39 - s) : s; mprev = fmaxf(chS[d * 72 + ci * 2] + mprev, chS[d * 72 + ci * 2 + 1]); }
.Lmn_skip:
	s_cmp_gt_i32 s3, 1
	s_cbranch_scc1 .LBB0_722
	s_cmp_gt_i32 s4, 3
	s_cselect_b32 s5, 39, 3
	s_sub_i32 s5, s5, s4
	s_cmp_eq_u32 s3, 0
	s_cselect_b64 vcc, -1, 0
	s_cselect_b32 s4, s4, s5
	v_mov_b32_e32 v6, 0
	s_cmp_lt_i32 s4, 1
	s_cbranch_scc1 .LBB0_719
	s_mul_i32 s5, s3, 0x120
	s_add_i32 s5, s5, 0x11320
	v_cmp_gt_u32_e64 s[6:7], 4, v62
	v_mov_b32_e32 v0, 39
	s_nop 1
	v_cndmask_b32_e64 v0, v0, 3, s[6:7]
	v_sub_u32_e32 v0, v0, v62
	v_cndmask_b32_e32 v0, v0, v62, vcc
	v_lshl_add_u32 v0, v0, 3, s5
	ds_read_b64 v[4:5], v0
	s_waitcnt lgkmcnt(0)
	v_readlane_b32 s6, v4, 0
	v_readlane_b32 s7, v5, 0
	v_readlane_b32 s8, v4, 1
	v_readlane_b32 s9, v5, 1
	v_add_f32_e32 v6, s6, v6
	v_max_f32_e32 v6, s7, v6
	s_cmp_eq_u32 s4, 1
	s_cbranch_scc1 .LBB0_719
	v_readlane_b32 s6, v4, 2
	v_readlane_b32 s7, v5, 2
	v_add_f32_e32 v6, s8, v6
	v_max_f32_e32 v6, s9, v6
	s_cmp_eq_u32 s4, 2
	s_cbranch_scc1 .LBB0_719
	v_readlane_b32 s8, v4, 3
	v_readlane_b32 s9, v5, 3
	v_add_f32_e32 v6, s6, v6
	v_max_f32_e32 v6, s7, v6
	s_cmp_eq_u32 s4, 3
	s_cbranch_scc1 .LBB0_719
	v_readlane_b32 s6, v4, 4
	v_readlane_b32 s7, v5, 4
	v_add_f32_e32 v6, s8, v6
	v_max_f32_e32 v6, s9, v6
	s_cmp_eq_u32 s4, 4
	s_cbranch_scc1 .LBB0_719
	v_readlane_b32 s8, v4, 5
	v_readlane_b32 s9, v5, 5
	v_add_f32_e32 v6, s6, v6
	v_max_f32_e32 v6, s7, v6
	s_cmp_eq_u32 s4, 5
	s_cbranch_scc1 .LBB0_719
	v_readlane_b32 s6, v4, 6
	v_readlane_b32 s7, v5, 6
	v_add_f32_e32 v6, s8, v6
	v_max_f32_e32 v6, s9, v6
	s_cmp_eq_u32 s4, 6
	s_cbranch_scc1 .LBB0_719
	v_readlane_b32 s8, v4, 7
	v_readlane_b32 s9, v5, 7
	v_add_f32_e32 v6, s6, v6
	v_max_f32_e32 v6, s7, v6
	s_cmp_eq_u32 s4, 7
	s_cbranch_scc1 .LBB0_719
	v_readlane_b32 s6, v4, 8
	v_readlane_b32 s7, v5, 8
	v_add_f32_e32 v6, s8, v6
	v_max_f32_e32 v6, s9, v6
	s_cmp_eq_u32 s4, 8
	s_cbranch_scc1 .LBB0_719
	v_readlane_b32 s8, v4, 9
	v_readlane_b32 s9, v5, 9
	v_add_f32_e32 v6, s6, v6
	v_max_f32_e32 v6, s7, v6
	s_cmp_eq_u32 s4, 9
	s_cbranch_scc1 .LBB0_719
	v_readlane_b32 s6, v4, 10
	v_readlane_b32 s7, v5, 10
	v_add_f32_e32 v6, s8, v6
	v_max_f32_e32 v6, s9, v6
	s_cmp_eq_u32 s4, 10
	s_cbranch_scc1 .LBB0_719
	v_readlane_b32 s8, v4, 11
	v_readlane_b32 s9, v5, 11
	v_add_f32_e32 v6, s6, v6
	v_max_f32_e32 v6, s7, v6
	s_cmp_eq_u32 s4, 11
	s_cbranch_scc1 .LBB0_719
	v_readlane_b32 s6, v4, 12
	v_readlane_b32 s7, v5, 12
	v_add_f32_e32 v6, s8, v6
	v_max_f32_e32 v6, s9, v6
	s_cmp_eq_u32 s4, 12
	s_cbranch_scc1 .LBB0_719
	v_readlane_b32 s8, v4, 13
	v_readlane_b32 s9, v5, 13
	v_add_f32_e32 v6, s6, v6
	v_max_f32_e32 v6, s7, v6
	s_cmp_eq_u32 s4, 13
	s_cbranch_scc1 .LBB0_719
	v_readlane_b32 s6, v4, 14
	v_readlane_b32 s7, v5, 14
	v_add_f32_e32 v6, s8, v6
	v_max_f32_e32 v6, s9, v6
	s_cmp_eq_u32 s4, 14
	s_cbranch_scc1 .LBB0_719
	v_readlane_b32 s8, v4, 15
	v_readlane_b32 s9, v5, 15
	v_add_f32_e32 v6, s6, v6
	v_max_f32_e32 v6, s7, v6
	s_cmp_eq_u32 s4, 15
	s_cbranch_scc1 .LBB0_719
	v_readlane_b32 s6, v4, 16
	v_readlane_b32 s7, v5, 16
	v_add_f32_e32 v6, s8, v6
	v_max_f32_e32 v6, s9, v6
	s_cmp_eq_u32 s4, 16
	s_cbranch_scc1 .LBB0_719
	v_readlane_b32 s8, v4, 17
	v_readlane_b32 s9, v5, 17
	v_add_f32_e32 v6, s6, v6
	v_max_f32_e32 v6, s7, v6
	s_cmp_eq_u32 s4, 17
	s_cbranch_scc1 .LBB0_719
	v_readlane_b32 s6, v4, 18
	v_readlane_b32 s7, v5, 18
	v_add_f32_e32 v6, s8, v6
	v_max_f32_e32 v6, s9, v6
	s_cmp_eq_u32 s4, 18
	s_cbranch_scc1 .LBB0_719
	v_readlane_b32 s8, v4, 19
	v_readlane_b32 s9, v5, 19
	v_add_f32_e32 v6, s6, v6
	v_max_f32_e32 v6, s7, v6
	s_cmp_eq_u32 s4, 19
	s_cbranch_scc1 .LBB0_719
	v_readlane_b32 s6, v4, 20
	v_readlane_b32 s7, v5, 20
	v_add_f32_e32 v6, s8, v6
	v_max_f32_e32 v6, s9, v6
	s_cmp_eq_u32 s4, 20
	s_cbranch_scc1 .LBB0_719
	v_readlane_b32 s8, v4, 21
	v_readlane_b32 s9, v5, 21
	v_add_f32_e32 v6, s6, v6
	v_max_f32_e32 v6, s7, v6
	s_cmp_eq_u32 s4, 21
	s_cbranch_scc1 .LBB0_719
	v_readlane_b32 s6, v4, 22
	v_readlane_b32 s7, v5, 22
	v_add_f32_e32 v6, s8, v6
	v_max_f32_e32 v6, s9, v6
	s_cmp_eq_u32 s4, 22
	s_cbranch_scc1 .LBB0_719
	v_readlane_b32 s8, v4, 23
	v_readlane_b32 s9, v5, 23
	v_add_f32_e32 v6, s6, v6
	v_max_f32_e32 v6, s7, v6
	s_cmp_eq_u32 s4, 23
	s_cbranch_scc1 .LBB0_719
	v_readlane_b32 s6, v4, 24
	v_readlane_b32 s7, v5, 24
	v_add_f32_e32 v6, s8, v6
	v_max_f32_e32 v6, s9, v6
	s_cmp_eq_u32 s4, 24
	s_cbranch_scc1 .LBB0_719
	v_readlane_b32 s8, v4, 25
	v_readlane_b32 s9, v5, 25
	v_add_f32_e32 v6, s6, v6
	v_max_f32_e32 v6, s7, v6
	s_cmp_eq_u32 s4, 25
	s_cbranch_scc1 .LBB0_719
	v_readlane_b32 s6, v4, 26
	v_readlane_b32 s7, v5, 26
	v_add_f32_e32 v6, s8, v6
	v_max_f32_e32 v6, s9, v6
	s_cmp_eq_u32 s4, 26
	s_cbranch_scc1 .LBB0_719
	v_readlane_b32 s8, v4, 27
	v_readlane_b32 s9, v5, 27
	v_add_f32_e32 v6, s6, v6
	v_max_f32_e32 v6, s7, v6
	s_cmp_eq_u32 s4, 27
	s_cbranch_scc1 .LBB0_719
	v_readlane_b32 s6, v4, 28
	v_readlane_b32 s7, v5, 28
	v_add_f32_e32 v6, s8, v6
	v_max_f32_e32 v6, s9, v6
	s_cmp_eq_u32 s4, 28
	s_cbranch_scc1 .LBB0_719
	v_readlane_b32 s8, v4, 29
	v_readlane_b32 s9, v5, 29
	v_add_f32_e32 v6, s6, v6
	v_max_f32_e32 v6, s7, v6
	s_cmp_eq_u32 s4, 29
	s_cbranch_scc1 .LBB0_719
	v_readlane_b32 s6, v4, 30
	v_readlane_b32 s7, v5, 30
	v_add_f32_e32 v6, s8, v6
	v_max_f32_e32 v6, s9, v6
	s_cmp_eq_u32 s4, 30
	s_cbranch_scc1 .LBB0_719
	v_readlane_b32 s8, v4, 31
	v_readlane_b32 s9, v5, 31
	v_add_f32_e32 v6, s6, v6
	v_max_f32_e32 v6, s7, v6
	s_cmp_eq_u32 s4, 31
	s_cbranch_scc1 .LBB0_719
	v_readlane_b32 s6, v4, 32
	v_readlane_b32 s7, v5, 32
	v_add_f32_e32 v6, s8, v6
	v_max_f32_e32 v6, s9, v6
	s_cmp_eq_u32 s4, 32
	s_cbranch_scc1 .LBB0_719
	v_readlane_b32 s8, v4, 33
	v_readlane_b32 s9, v5, 33
	v_add_f32_e32 v6, s6, v6
	v_max_f32_e32 v6, s7, v6
	s_cmp_eq_u32 s4, 33
	s_cbranch_scc1 .LBB0_719
	v_readlane_b32 s6, v4, 34
	v_readlane_b32 s7, v5, 34
	v_add_f32_e32 v6, s8, v6
	v_max_f32_e32 v6, s9, v6
	s_cmp_eq_u32 s4, 34
	s_cbranch_scc1 .LBB0_719
	s_nop 1
	v_add_f32_e32 v6, s6, v6
	v_max_f32_e32 v6, s7, v6
